# stack15: in grid barriers 2..9 the last arriver of an XCD increments the cross-XCD counter without return and goes straight to polling (no flag publish)
# speedup vs baseline: 1.0022x; 1.0022x over previous
; DI void grid_barrier_xcd(unsigned* bar, const unsigned gen, const unsigned my_xcc, const unsigned n_local, const unsigned n_xcds) {
;     ...
;     const unsigned old = __hip_atomic_fetch_add(xcnt, 1u, __ATOMIC_RELAXED, __HIP_MEMORY_SCOPE_AGENT);
;     if (old + 1u == gen * n_local) {
;       __builtin_amdgcn_fence(__ATOMIC_RELEASE, "agent");
;       asm volatile("s_waitcnt vmcnt(0)" ::: "memory");
;       const unsigned t = __hip_atomic_fetch_add(top, 1u, __ATOMIC_RELAXED, __HIP_MEMORY_SCOPE_AGENT);
;       if (t + 1u == gen * n_xcds) __hip_atomic_store(rel, gen, __ATOMIC_RELAXED, __HIP_MEMORY_SCOPE_AGENT);
;     }
.LBB0_130:
	s_or_b64 exec, exec, s[10:11]
	s_waitcnt vmcnt(0)
	buffer_inv sc1
	v_readfirstlane_b32 s0, v2
	s_add_u32 s10, s72, 0x1ec00b00
	v_mul_lo_u32 v2, v201, s3
	v_add3_u32 v1, s0, v1, 1
	s_addc_u32 s11, s73, 0
	v_cmp_eq_u32_e32 vcc, v1, v2
	s_and_saveexec_b64 s[12:13], vcc
	s_cbranch_execz .LBB0_135
	s_mov_b64 s[14:15], exec
	buffer_wbl2 sc1
	s_waitcnt vmcnt(0)
	v_mbcnt_lo_u32_b32 v1, s14, 0
	v_mbcnt_hi_u32_b32 v1, s15, v1
	v_cmp_eq_u32_e32 vcc, 0, v1
	s_and_saveexec_b64 s[16:17], vcc
	s_cbranch_execz .LBB0_133
	s_bcnt1_i32_b64 s0, s[14:15]
	v_mov_b32_e32 v2, 0x1ec00000
	v_mov_b32_e32 v3, s0
	global_atomic_add v2, v3, s[72:73] offset:2560
.LBB0_133:
	s_or_b64 exec, exec, s[16:17]
.LBB0_135:
	s_or_b64 exec, exec, s[12:13]
	v_readfirstlane_b32 s101, v200
	s_mul_i32 s101, s101, s3
	s_add_i32 s101, s101, -1
	s_sub_u32 s10, s10, 0x100
	s_subb_u32 s11, s11, 0
	s_mov_b32 s0, 0x1000000
	v_mov_b32_e32 v1, 0
	s_branch .LBB0_138

; DI void grid_barrier_xcd(unsigned* bar, const unsigned gen, const unsigned my_xcc, const unsigned n_local, const unsigned n_xcds) {
;     ...
;     const unsigned old = __hip_atomic_fetch_add(xcnt, 1u, __ATOMIC_RELAXED, __HIP_MEMORY_SCOPE_AGENT);
;     if (old + 1u == gen * n_local) {
;       __builtin_amdgcn_fence(__ATOMIC_RELEASE, "agent");
;       asm volatile("s_waitcnt vmcnt(0)" ::: "memory");
;       const unsigned t = __hip_atomic_fetch_add(top, 1u, __ATOMIC_RELAXED, __HIP_MEMORY_SCOPE_AGENT);
;       if (t + 1u == gen * n_xcds) __hip_atomic_store(rel, gen, __ATOMIC_RELAXED, __HIP_MEMORY_SCOPE_AGENT);
;     }
.LBB0_263:
	s_or_b64 exec, exec, s[10:11]
	s_waitcnt vmcnt(0)
	buffer_inv sc1
	v_readfirstlane_b32 s0, v2
	s_add_u32 s10, s72, 0x1ec00b00
	v_mul_lo_u32 v2, v201, s4
	v_add3_u32 v1, s0, v1, 1
	s_addc_u32 s11, s73, 0
	v_cmp_eq_u32_e32 vcc, v1, v2
	s_and_saveexec_b64 s[12:13], vcc
	s_cbranch_execz .LBB0_268
	s_mov_b64 s[14:15], exec
	buffer_wbl2 sc1
	s_waitcnt vmcnt(0)
	v_mbcnt_lo_u32_b32 v1, s14, 0
	v_mbcnt_hi_u32_b32 v1, s15, v1
	v_cmp_eq_u32_e32 vcc, 0, v1
	s_and_saveexec_b64 s[16:17], vcc
	s_cbranch_execz .LBB0_266
	s_bcnt1_i32_b64 s0, s[14:15]
	v_mov_b32_e32 v2, 0x1ec00000
	v_mov_b32_e32 v3, s0
	global_atomic_add v2, v3, s[72:73] offset:2560
.LBB0_266:
	s_or_b64 exec, exec, s[16:17]
.LBB0_268:
	s_or_b64 exec, exec, s[12:13]
	v_readfirstlane_b32 s101, v200
	s_mul_i32 s101, s101, s4
	s_add_i32 s101, s101, -1
	s_sub_u32 s10, s10, 0x100
	s_subb_u32 s11, s11, 0
	s_mov_b32 s0, 0x1000000
	v_mov_b32_e32 v1, 0
	s_branch .LBB0_271

; DI void grid_barrier_xcd(unsigned* bar, const unsigned gen, const unsigned my_xcc, const unsigned n_local, const unsigned n_xcds) {
;     ...
;     const unsigned old = __hip_atomic_fetch_add(xcnt, 1u, __ATOMIC_RELAXED, __HIP_MEMORY_SCOPE_AGENT);
;     if (old + 1u == gen * n_local) {
;       __builtin_amdgcn_fence(__ATOMIC_RELEASE, "agent");
;       asm volatile("s_waitcnt vmcnt(0)" ::: "memory");
;       const unsigned t = __hip_atomic_fetch_add(top, 1u, __ATOMIC_RELAXED, __HIP_MEMORY_SCOPE_AGENT);
;       if (t + 1u == gen * n_xcds) __hip_atomic_store(rel, gen, __ATOMIC_RELAXED, __HIP_MEMORY_SCOPE_AGENT);
;     }
.LBB0_324:
	s_or_b64 exec, exec, s[8:9]
	s_waitcnt vmcnt(0)
	buffer_inv sc1
	v_readfirstlane_b32 s0, v2
	s_add_u32 s8, s72, 0x1ec00b00
	v_mul_lo_u32 v2, v201, s5
	v_add3_u32 v1, s0, v1, 1
	s_addc_u32 s9, s73, 0
	v_cmp_eq_u32_e32 vcc, v1, v2
	s_and_saveexec_b64 s[12:13], vcc
	s_cbranch_execz .LBB0_329
	s_mov_b64 s[14:15], exec
	buffer_wbl2 sc1
	s_waitcnt vmcnt(0)
	v_mbcnt_lo_u32_b32 v1, s14, 0
	v_mbcnt_hi_u32_b32 v1, s15, v1
	v_cmp_eq_u32_e32 vcc, 0, v1
	s_and_saveexec_b64 s[16:17], vcc
	s_cbranch_execz .LBB0_327
	s_bcnt1_i32_b64 s0, s[14:15]
	v_mov_b32_e32 v2, 0x1ec00000
	v_mov_b32_e32 v3, s0
	global_atomic_add v2, v3, s[72:73] offset:2560
.LBB0_327:
	s_or_b64 exec, exec, s[16:17]
.LBB0_329:
	s_or_b64 exec, exec, s[12:13]
	v_readfirstlane_b32 s101, v200
	s_mul_i32 s101, s101, s5
	s_add_i32 s101, s101, -1
	s_sub_u32 s8, s8, 0x100
	s_subb_u32 s9, s9, 0
	s_mov_b32 s0, 0x1000000
	v_mov_b32_e32 v1, 0
	s_branch .LBB0_332

; DI void grid_barrier_xcd(unsigned* bar, const unsigned gen, const unsigned my_xcc, const unsigned n_local, const unsigned n_xcds) {
;     ...
;     const unsigned old = __hip_atomic_fetch_add(xcnt, 1u, __ATOMIC_RELAXED, __HIP_MEMORY_SCOPE_AGENT);
;     if (old + 1u == gen * n_local) {
;       __builtin_amdgcn_fence(__ATOMIC_RELEASE, "agent");
;       asm volatile("s_waitcnt vmcnt(0)" ::: "memory");
;       const unsigned t = __hip_atomic_fetch_add(top, 1u, __ATOMIC_RELAXED, __HIP_MEMORY_SCOPE_AGENT);
;       if (t + 1u == gen * n_xcds) __hip_atomic_store(rel, gen, __ATOMIC_RELAXED, __HIP_MEMORY_SCOPE_AGENT);
;     }
.LBB0_373:
	s_or_b64 exec, exec, s[8:9]
	s_waitcnt vmcnt(0)
	buffer_inv sc1
	v_readfirstlane_b32 s0, v2
	s_add_u32 s8, s72, 0x1ec00b00
	v_mul_lo_u32 v2, v201, s3
	v_add3_u32 v1, s0, v1, 1
	s_addc_u32 s9, s73, 0
	v_cmp_eq_u32_e32 vcc, v1, v2
	s_and_saveexec_b64 s[12:13], vcc
	s_cbranch_execz .LBB0_378
	s_mov_b64 s[14:15], exec
	buffer_wbl2 sc1
	s_waitcnt vmcnt(0)
	v_mbcnt_lo_u32_b32 v1, s14, 0
	v_mbcnt_hi_u32_b32 v1, s15, v1
	v_cmp_eq_u32_e32 vcc, 0, v1
	s_and_saveexec_b64 s[16:17], vcc
	s_cbranch_execz .LBB0_376
	s_bcnt1_i32_b64 s0, s[14:15]
	v_mov_b32_e32 v2, 0x1ec00000
	v_mov_b32_e32 v3, s0
	global_atomic_add v2, v3, s[72:73] offset:2560
.LBB0_376:
	s_or_b64 exec, exec, s[16:17]
.LBB0_378:
	s_or_b64 exec, exec, s[12:13]
	v_readfirstlane_b32 s101, v200
	s_mul_i32 s101, s101, s3
	s_add_i32 s101, s101, -1
	s_sub_u32 s8, s8, 0x100
	s_subb_u32 s9, s9, 0
	s_mov_b32 s0, 0x1000000
	v_mov_b32_e32 v1, 0
	s_branch .LBB0_381

; DI void grid_barrier_xcd(unsigned* bar, const unsigned gen, const unsigned my_xcc, const unsigned n_local, const unsigned n_xcds) {
;     ...
;       const unsigned t = __hip_atomic_fetch_add(top, 1u, __ATOMIC_RELAXED, __HIP_MEMORY_SCOPE_AGENT);
;       if (t + 1u == gen * n_xcds) __hip_atomic_store(rel, gen, __ATOMIC_RELAXED, __HIP_MEMORY_SCOPE_AGENT);
;     }
.LBB0_436:
	s_or_b64 exec, exec, s[16:17]
.LBB0_438:
	s_or_b64 exec, exec, s[12:13]
	v_readfirstlane_b32 s101, v200
	s_mul_i32 s101, s101, s4
	s_add_i32 s101, s101, -1
	s_sub_u32 s10, s10, 0x100
	s_subb_u32 s11, s11, 0
	s_mov_b32 s0, 0x1000000
	v_mov_b32_e32 v1, 0
	s_branch .LBB0_441

; DI void grid_barrier_xcd(unsigned* bar, const unsigned gen, const unsigned my_xcc, const unsigned n_local, const unsigned n_xcds) {
;     ...
;     const unsigned old = __hip_atomic_fetch_add(xcnt, 1u, __ATOMIC_RELAXED, __HIP_MEMORY_SCOPE_AGENT);
;     if (old + 1u == gen * n_local) {
;       __builtin_amdgcn_fence(__ATOMIC_RELEASE, "agent");
;       asm volatile("s_waitcnt vmcnt(0)" ::: "memory");
;       const unsigned t = __hip_atomic_fetch_add(top, 1u, __ATOMIC_RELAXED, __HIP_MEMORY_SCOPE_AGENT);
;       if (t + 1u == gen * n_xcds) __hip_atomic_store(rel, gen, __ATOMIC_RELAXED, __HIP_MEMORY_SCOPE_AGENT);
;     }
.LBB0_482:
	s_or_b64 exec, exec, s[10:11]
	s_waitcnt vmcnt(0)
	buffer_inv sc1
	v_readfirstlane_b32 s0, v3
	s_add_u32 s10, s72, 0x1ec00b00
	v_mul_lo_u32 v3, v201, s5
	v_add3_u32 v2, s0, v2, 1
	s_addc_u32 s11, s73, 0
	v_cmp_eq_u32_e32 vcc, v2, v3
	s_and_saveexec_b64 s[12:13], vcc
	s_cbranch_execz .LBB0_487
	s_mov_b64 s[14:15], exec
	buffer_wbl2 sc1
	s_waitcnt vmcnt(0)
	v_mbcnt_lo_u32_b32 v2, s14, 0
	v_mbcnt_hi_u32_b32 v2, s15, v2
	v_cmp_eq_u32_e32 vcc, 0, v2
	s_and_saveexec_b64 s[16:17], vcc
	s_cbranch_execz .LBB0_485
	s_bcnt1_i32_b64 s0, s[14:15]
	v_mov_b32_e32 v3, 0x1ec00000
	v_mov_b32_e32 v4, s0
	global_atomic_add v3, v4, s[72:73] offset:2560
.LBB0_485:
	s_or_b64 exec, exec, s[16:17]
.LBB0_487:
	s_or_b64 exec, exec, s[12:13]
	v_readfirstlane_b32 s101, v200
	s_mul_i32 s101, s101, s5
	s_add_i32 s101, s101, -1
	s_sub_u32 s10, s10, 0x100
	s_subb_u32 s11, s11, 0
	s_mov_b32 s0, 0x1000000
	v_mov_b32_e32 v2, 0
	s_branch .LBB0_490

; DI void grid_barrier_xcd(unsigned* bar, const unsigned gen, const unsigned my_xcc, const unsigned n_local, const unsigned n_xcds) {
;     ...
;     const unsigned old = __hip_atomic_fetch_add(xcnt, 1u, __ATOMIC_RELAXED, __HIP_MEMORY_SCOPE_AGENT);
;     if (old + 1u == gen * n_local) {
;       __builtin_amdgcn_fence(__ATOMIC_RELEASE, "agent");
;       asm volatile("s_waitcnt vmcnt(0)" ::: "memory");
;       const unsigned t = __hip_atomic_fetch_add(top, 1u, __ATOMIC_RELAXED, __HIP_MEMORY_SCOPE_AGENT);
;       if (t + 1u == gen * n_xcds) __hip_atomic_store(rel, gen, __ATOMIC_RELAXED, __HIP_MEMORY_SCOPE_AGENT);
;     }
.LBB0_544:
	s_or_b64 exec, exec, s[10:11]
	s_waitcnt vmcnt(0)
	buffer_inv sc1
	v_readfirstlane_b32 s0, v3
	s_add_u32 s10, s72, 0x1ec00b00
	v_mul_lo_u32 v3, v201, s3
	v_add3_u32 v2, s0, v2, 1
	s_addc_u32 s11, s73, 0
	v_cmp_eq_u32_e32 vcc, v2, v3
	s_and_saveexec_b64 s[12:13], vcc
	s_cbranch_execz .LBB0_549
	s_mov_b64 s[14:15], exec
	buffer_wbl2 sc1
	s_waitcnt vmcnt(0)
	v_mbcnt_lo_u32_b32 v2, s14, 0
	v_mbcnt_hi_u32_b32 v2, s15, v2
	v_cmp_eq_u32_e32 vcc, 0, v2
	s_and_saveexec_b64 s[16:17], vcc
	s_cbranch_execz .LBB0_547
	s_bcnt1_i32_b64 s0, s[14:15]
	v_mov_b32_e32 v3, 0x1ec00000
	v_mov_b32_e32 v4, s0
	global_atomic_add v3, v4, s[72:73] offset:2560
.LBB0_547:
	s_or_b64 exec, exec, s[16:17]
.LBB0_549:
	s_or_b64 exec, exec, s[12:13]
	v_readfirstlane_b32 s101, v200
	s_mul_i32 s101, s101, s3
	s_add_i32 s101, s101, -1
	s_sub_u32 s10, s10, 0x100
	s_subb_u32 s11, s11, 0
	s_mov_b32 s0, 0x1000000
	v_mov_b32_e32 v2, 0
	s_branch .LBB0_552

; DI void grid_barrier_xcd(unsigned* bar, const unsigned gen, const unsigned my_xcc, const unsigned n_local, const unsigned n_xcds) {
;     ...
;     const unsigned old = __hip_atomic_fetch_add(xcnt, 1u, __ATOMIC_RELAXED, __HIP_MEMORY_SCOPE_AGENT);
;     if (old + 1u == gen * n_local) {
;       __builtin_amdgcn_fence(__ATOMIC_RELEASE, "agent");
;       asm volatile("s_waitcnt vmcnt(0)" ::: "memory");
;       const unsigned t = __hip_atomic_fetch_add(top, 1u, __ATOMIC_RELAXED, __HIP_MEMORY_SCOPE_AGENT);
;       if (t + 1u == gen * n_xcds) __hip_atomic_store(rel, gen, __ATOMIC_RELAXED, __HIP_MEMORY_SCOPE_AGENT);
;     }
.LBB0_591:
	s_or_b64 exec, exec, s[4:5]
	s_add_u32 s4, s72, 0x1ec00b00
	s_addc_u32 s5, s73, 0
	s_add_i32 s0, s3, 1
	s_waitcnt vmcnt(0)
	buffer_inv sc1
	v_readfirstlane_b32 s1, v2
	v_mul_lo_u32 v2, v201, s0
	s_nop 0
	v_add3_u32 v1, s1, v1, 1
	v_cmp_eq_u32_e32 vcc, v1, v2
	s_and_saveexec_b64 s[10:11], vcc
	s_cbranch_execz .LBB0_596
	s_mov_b64 s[12:13], exec
	buffer_wbl2 sc1
	s_waitcnt vmcnt(0)
	v_mbcnt_lo_u32_b32 v1, s12, 0
	v_mbcnt_hi_u32_b32 v1, s13, v1
	v_cmp_eq_u32_e32 vcc, 0, v1
	s_and_saveexec_b64 s[14:15], vcc
	s_cbranch_execz .LBB0_594
	s_bcnt1_i32_b64 s1, s[12:13]
	v_mov_b32_e32 v2, 0x1ec00000
	v_mov_b32_e32 v3, s1
	global_atomic_add v2, v3, s[72:73] offset:2560
.LBB0_594:
	s_or_b64 exec, exec, s[14:15]
.LBB0_596:
	s_or_b64 exec, exec, s[10:11]
	v_readfirstlane_b32 s101, v200
	s_mul_i32 s101, s101, s0
	s_add_i32 s101, s101, -1
	s_sub_u32 s4, s4, 0x100
	s_subb_u32 s5, s5, 0
	s_mov_b32 s0, 0x1000000
	v_mov_b32_e32 v1, 0
	s_branch .LBB0_599
